# byte-placement trial: merge phase code shifted by 16 bytes (M K-loop head at a 64-byte boundary), code after the phase kept in place
# speedup vs baseline: 1.0037x; 1.0037x over previous
; template <int MB, bool PF2 = true>
; DI void gemm_main(const u16* __restrict__ A, int lda, const u16* __restrict__ B, int ldb, int K, f32x16 (&acc)[MB][2], GemmLds* s, int tid) {
;   const int lane = tid & 63, w = tid >> 6, r = lane & 31, h = lane >> 5, wm = w >> 1, wn = w & 1;
;   const int srow = tid >> 3, skc = (tid & 7) * 8;
;   const unsigned oa0 = (unsigned)(srow * lda + skc) * 2u, oa1 = oa0 + 64u * lda, oa2 = oa0 + 128u * lda, oa3 = oa0 + 192u * lda;
;   const unsigned ob0 = (unsigned)(srow * ldb + skc) * 2u, ob1 = ob0 + 64u * ldb, ob2 = ob0 + 128u * ldb, ob3 = ob0 + 192u * ldb;
; DI void phase_merge(const Params& p, int l, char* smem, int tid) {
;   const int lane = tid & 63, w = tid >> 6, r = lane & 31, h = lane >> 5, wm = w >> 1, wn = w & 1;
;   GemmLds* s = (GemmLds*)smem;
;   u16* ACC = p.Pk;
;   const bool dyn = (l == 0);
;   unsigned* qc = p.bar + 4096 + 320;
;   for (int it = (dyn ? fetch_item(qc, smem) : (int)blockIdx.x); it < 544 * 8; it = (dyn ? fetch_item(qc, smem) : it + (int)gridDim.x)) {
.LBB0_1140:
	s_or_b64 exec, exec, s[0:1]
	v_readlane_b32 s2, v254, 17
	v_readlane_b32 s3, v254, 18
	v_mov_b32_e32 v0, v206
	s_andn2_b64 vcc, exec, s[2:3]
	v_cndmask_b32_e64 v2, 0, 1, s[2:3]
	v_cmp_ne_u32_e64 s[0:1], 1, v2
	v_mov_b32_e32 v149, s48
	s_waitcnt lgkmcnt(0)
	s_barrier
	v_readlane_b32 s18, v254, 19
	v_and_b32_e32 v147, 63, v206
	v_lshrrev_b32_e32 v149, 6, v206
	v_lshrrev_b32_e32 v151, 3, v147
	v_lshl_add_u32 v151, v149, 5, v151
	v_lshlrev_b32_e32 v151, 11, v151
	v_and_b32_e32 v153, 7, v147
	v_lshrrev_b32_e32 v147, 4, v147
	v_xor_b32_e32 v153, v153, v147
	v_lshl_or_b32 v200, v153, 4, v151
	v_xor_b32_e32 v201, 64, v200
	v_add_u32_e32 v201, 16384, v201
	v_add_u32_e32 v202, 32768, v200
	v_add_u32_e32 v203, 32768, v201
	v_and_b32_e32 v147, 63, v206
	v_lshrrev_b32_e32 v149, 6, v206
	v_lshrrev_b32_e32 v151, 3, v147
	v_lshl_add_u32 v151, v149, 5, v151
	v_lshlrev_b32_e32 v151, 9, v151
	v_and_b32_e32 v153, 7, v147
	v_lshrrev_b32_e32 v147, 4, v147
	v_xor_b32_e32 v153, v153, v147
	v_lshl_or_b32 v130, v153, 4, v151
	v_xor_b32_e32 v131, 64, v130
	v_add_u32_e32 v131, 4096, v131
	v_add_u32_e32 v132, 8192, v130
	v_add_u32_e32 v133, 8192, v131
	v_lshrrev_b32_e32 v204, 6, v206
	v_and_b32_e32 v147, 31, v206
	v_bfe_u32 v149, v206, 5, 1
	v_bfe_u32 v151, v147, 1, 3
	v_xor_b32_e32 v151, v151, v149
	v_lshlrev_b32_e32 v151, 4, v151
	v_lshl_or_b32 v151, v147, 7, v151
	v_lshrrev_b32_e32 v153, 7, v206
	v_lshl_add_u32 v138, v153, 13, v151
	v_bfe_u32 v153, v206, 6, 1
	v_lshl_add_u32 v142, v153, 13, v151
	v_add_u32_e32 v142, 0x4000, v142
	v_xor_b32_e32 v139, 32, v138
	v_xor_b32_e32 v143, 32, v142
	v_xor_b32_e32 v140, 64, v138
	v_xor_b32_e32 v144, 64, v142
	v_xor_b32_e32 v141, 96, v138
	v_xor_b32_e32 v145, 96, v142
	v_and_b32_e32 v147, 31, v206
	v_lshrrev_b32_e32 v149, 7, v206
	v_lshl_add_u32 v147, v149, 6, v147
	v_lshlrev_b32_e32 v147, 11, v147
	v_bfe_u32 v149, v206, 6, 1
	v_lshlrev_b32_e32 v149, 7, v149
	v_bfe_u32 v151, v206, 5, 1
	v_lshl_or_b32 v149, v151, 3, v149
	v_or_b32_e32 v146, v147, v149
	v_lshrrev_b32_e32 v147, 6, v206
	v_mul_u32_u24_e32 v147, 0x2400, v147
	v_and_b32_e32 v149, 31, v206
	v_mul_u32_u24_e32 v149, 0x90, v149
	v_bfe_u32 v151, v206, 5, 1
	v_lshl_add_u32 v149, v151, 3, v149
	v_add_u32_e32 v134, v147, v149
	v_bfe_u32 v149, v206, 3, 3
	v_mul_u32_u24_e32 v149, 0x90, v149
	v_and_b32_e32 v151, 7, v206
	v_lshl_add_u32 v149, v151, 4, v149
	v_add_u32_e32 v135, v147, v149
	v_bfe_u32 v147, v206, 3, 3
	v_lshrrev_b32_e32 v149, 7, v206
	v_lshl_add_u32 v147, v149, 6, v147
	v_mul_u32_u24_e32 v147, 0x800, v147
	v_bfe_u32 v149, v206, 6, 1
	v_lshlrev_b32_e32 v149, 7, v149
	v_and_b32_e32 v151, 7, v206
	v_lshl_or_b32 v149, v151, 4, v149
	v_add_u32_e32 v136, v147, v149
	v_readfirstlane_b32 s10, v204
	s_lshl_b32 s10, s10, 12
	s_lshl_b32 s6, s18, 23
	s_add_u32 s14, s96, 0x1b720000
	s_addc_u32 s15, s97, 0
	s_add_u32 s14, s14, s6
	s_addc_u32 s15, s15, 0
	s_lshl_b32 s6, s18, 21
	s_add_u32 s16, s96, 0x1c800000
	s_addc_u32 s17, s97, 0
	s_add_u32 s16, s16, s6
	s_addc_u32 s17, s17, 0
	s_mov_b32 s12, s48
	s_nop 0
	s_nop 0
	s_nop 0
	s_nop 0

; DI int launder_i(int v) { asm volatile("" : "+v"(v)); return v; }
; #define GRID_BAR() xcd_barrier((unsigned*)(ka.ws + OFF_BAR), xb_xcc_id(), (volatile unsigned*)&xb_words)
; DI void xcd_barrier(unsigned* bar, unsigned x, volatile unsigned* st) {
;   asm volatile("s_waitcnt vmcnt(0)" ::: "memory");
;   __syncthreads();
; __global__ void __launch_bounds__(256, 2) mega_kernel(KArgs ka) {
;     ...
;     { Params p = make_params(ka); phase_merge(p, l, smem, launder_i(tid)); } GRID_BAR();
.Lmg_done:
	s_nop 0
	s_nop 0
	s_nop 0
	s_nop 0
	s_nop 0
	s_nop 0
	s_nop 0
	s_nop 0
	s_nop 0
	s_nop 0
	s_nop 0
	s_nop 0
	s_waitcnt vmcnt(0) lgkmcnt(0)
